# gla_pre inner loop: removed never-taken denormal/inf guards around log(1+e) (bit-identical), on top of NA group queue
# baseline (speedup 1.0000x reference)
; __device__ __forceinline__ unsigned f2bf(float f) { unsigned u = __builtin_bit_cast(unsigned, f); return (u + 0x7fffu + ((u >> 16) & 1u)) >> 16; }
; __device__ __forceinline__ float log_sigmoid(float x) { return fminf(x, 0.f) - __logf(1.0f + __expf(-fabsf(x))); }
; __device__ __forceinline__ void gla_pre(const Params& p, LAS unsigned char* lds, int wv) {
;     ...
;           for (int st = 0; st < c; ++st) { const int s = dr == 0 ? st : c - 1 - st;
;               float x = gb;
; #pragma unroll
;               for (int r = 0; r < 16; ++r) x += lrs[s * 32 + dr * 16 + r] * gu[r];
;               run += log_sigmoid(x) * (1.0f / 16.0f);
;               const float E = __expf(run);
;               const float qv = bf1(qs[s * 256 + d]) * E, kv = bf1(ks[s * 256 + d]) * __builtin_amdgcn_rcpf(E);
;               qo[(size_t)(g0 + s) * ldo + h * 256 + d] = (bf16_t)f2bf(qv); ko[(size_t)(g0 + s) * ldo + h * 256 + d] = (bf16_t)f2bf(kv); }
;           elast[((size_t)((dr * 2 + b) * 257 + ci) * 4 + h) * 256 + d] = __expf(run); }
.LBB0_1639:
	v_mov_b32_e32 v78, s10
	v_mov_b32_e32 v79, s11
	v_cndmask_b32_e64 v78, v78, v79, s[8:9]
	v_lshlrev_b32_e32 v80, 1, v14
	v_lshl_add_u32 v90, v78, 7, v63
	v_lshl_or_b32 v94, v78, 9, v80
	v_add_u32_e32 v95, s21, v78
	ds_read_b128 v[78:81], v90
	ds_read_b128 v[82:85], v90 offset:16
	ds_read_b128 v[86:89], v90 offset:32
	ds_read_b128 v[90:93], v90 offset:48
	v_add_u32_e32 v96, 0, v94
	s_waitcnt lgkmcnt(3)
	v_fma_f32 v78, v57, v78, v76
	v_fmac_f32_e32 v78, v59, v79
	v_fmac_f32_e32 v78, v60, v80
	v_fmac_f32_e32 v78, v61, v81
	s_waitcnt lgkmcnt(2)
	v_fmac_f32_e32 v78, v74, v82
	v_pk_mul_f32 v[84:85], v[0:1], v[84:85]
	v_fmac_f32_e32 v78, v75, v83
	v_add_f32_e32 v78, v78, v84
	s_waitcnt lgkmcnt(1)
	v_pk_mul_f32 v[86:87], v[2:3], v[86:87]
	v_add_f32_e32 v78, v78, v85
	v_add_f32_e32 v78, v78, v86
	v_pk_mul_f32 v[88:89], v[4:5], v[88:89]
	v_add_f32_e32 v78, v78, v87
	v_add_f32_e32 v78, v78, v88
	s_waitcnt lgkmcnt(0)
	v_pk_mul_f32 v[90:91], v[6:7], v[90:91]
	v_add_f32_e32 v78, v78, v89
	v_add_f32_e32 v78, v78, v90
	v_pk_mul_f32 v[92:93], v[8:9], v[92:93]
	v_add_f32_e32 v78, v78, v91
	v_add_f32_e32 v78, v78, v92
	v_add_f32_e32 v78, v78, v93
	v_min_f32_e32 v79, 0, v78
	v_mul_f32_e64 v78, |v78|, s13
	v_exp_f32_e32 v78, v78
	ds_read_u16 v98, v96
	ds_read_u16 v99, v96 offset:32768
	v_mad_i64_i32 v[94:95], s[22:23], v20, v95, v[10:11]
	v_add_f32_e32 v78, 1.0, v78
	v_lshlrev_b64 v[94:95], 1, v[94:95]
	v_lshl_add_u64 v[96:97], v[16:17], 0, v[94:95]
	v_log_f32_e32 v78, v78
	s_add_i32 s11, s11, 1
	s_add_i32 s10, s10, -1
	v_mul_f32_e32 v81, 0x3f317217, v78
	v_fma_f32 v81, v78, s15, -v81
	v_fmac_f32_e32 v81, 0x3377d1cf, v78
	v_fmac_f32_e32 v81, 0x3f317217, v78
	s_cmp_eq_u32 s10, -1
	v_lshl_add_u64 v[94:95], v[18:19], 0, v[94:95]
	v_sub_f32_e32 v78, v79, v81
	v_fmac_f32_e32 v77, 0x3d800000, v78
	v_mul_f32_e32 v78, 0x3fb8aa3b, v77
	v_exp_f32_e32 v78, v78
	s_waitcnt lgkmcnt(1)
	v_lshlrev_b32_e32 v79, 16, v98
	s_waitcnt lgkmcnt(0)
	v_lshlrev_b32_e32 v80, 16, v99
	v_rcp_f32_e32 v81, v78
	v_mul_f32_e32 v79, v78, v79
	v_bfe_u32 v82, v79, 16, 1
	v_add3_u32 v79, v79, v82, s17
	global_store_short_d16_hi v[96:97], v79, off
	v_mul_f32_e32 v79, v81, v80
	v_bfe_u32 v80, v79, 16, 1
	v_add3_u32 v79, v79, v80, s17
	global_store_short_d16_hi v[94:95], v79, off
	s_cbranch_scc0 .LBB0_1639
	v_add_u32_e32 v0, s19, v64
	v_lshl_add_u32 v0, v0, 8, v0
	v_add_u32_e32 v0, s20, v0
	v_ashrrev_i32_e32 v1, 31, v0
	v_lshlrev_b64 v[0:1], 12, v[0:1]
	v_lshl_add_u64 v[0:1], s[72:73], 0, v[0:1]
	v_lshl_add_u64 v[0:1], v[0:1], 0, s[0:1]
	v_mov_b32_e32 v59, v11
	s_add_i32 s18, s18, s96
	v_lshl_add_u64 v[0:1], v[0:1], 0, v[58:59]
	s_cmpk_gt_i32 s18, 0x807
	global_store_dword v[0:1], v78, off
	s_barrier
	s_cbranch_scc0 .LBB0_1628
